# indexer: pass 0 stores fp32 scores (scratch in d_out, dead until the last phase), pass 1 main loop reloads them instead of recomputing 8 MFMA + 64 VALU per tile
# speedup vs baseline: 1.0035x; 1.0035x over previous
; DI void idx_job(const Params& p, int b, int qg, unsigned char* smem) {
;   int tid_ = threadIdx.x & 255; asm volatile("" : "+v"(tid_));
;   const int tid = tid_, lane = tid & 63, wave = tid >> 6, lm = lane & 15, lg = lane >> 4;
;   u32* hist = (u32*)smem;
;   u32* maskw = (u32*)(smem + 32768);
;   u32* cand = (u32*)(smem + 41216);
;   u32* ccnt = (u32*)(smem + 49408);
;   u32* binA = ccnt + 16; u32* needB = ccnt + 32; u32* binB = ccnt + 48; u32* needC = ccnt + 64;
;   const int t0 = qg * 16, ntile = qg + 1, tq = t0 + lm;
;   const bool selall = tq + 1 <= 256;
;   bf16x8 qf[8];
;   float wq[8];
;   {
;     const u16* qr = p.qix + (size_t)(b * TP + tq) * 256 + lg * 8;
;     const float* wr = p.wix + (size_t)(b * TP + tq) * 8;
; #pragma unroll
;     for (int j = 0; j < 8; ++j) { qf[j] = *(const bf16x8*)(qr + j * 32); wq[j] = wr[j]; }
;   }
;   for (int i = tid; i < 8192 + 2112; i += 256) hist[i] = 0u;
;   if (tid < 80) ccnt[tid] = 0u;
;   __syncthreads();
;   const u16* kbase = p.kix + (size_t)b * TP * 32;
;   const f32x4 z4 = {0.f, 0.f, 0.f, 0.f};
;   const u16* kp = kbase + (size_t)lm * 32 + lg * 8;
.LBB0_388:
	s_andn2_saveexec_b64 s[56:57], s[2:3]
	s_cbranch_execz .LBB0_912
	s_waitcnt vmcnt(1)
	v_and_b32_e32 v42, 7, v0
	v_ashrrev_i32_e32 v0, 3, v0
	v_mov_b32_e32 v86, v196
	v_sub_u32_e32 v97, 0x107, v0
	s_load_dwordx16 s[60:75], s[0:1], 0x108
	s_load_dwordx2 s[90:91], s[0:1], 0xc0
	s_load_dwordx2 s[92:93], s[0:1], 0x150
	v_and_b32_e32 v88, 15, v86
	v_lshlrev_b32_e32 v87, 4, v97
	v_or_b32_e32 v108, v88, v87
	s_movk_i32 s2, 0x1080
	v_mad_u32_u24 v0, v42, s2, v108
	v_lshlrev_b64 v[2:3], 9, v[0:1]
	s_waitcnt lgkmcnt(0)
	v_readlane_b32 s88, v253, 0
	v_readfirstlane_b32 s89, v167
	v_lshlrev_b32_e32 v250, 4, v207
	v_mov_b32_e32 v251, 0
	s_nop 1
	s_lshl_b32 s88, s88, 1
	s_add_i32 s88, s88, s89
	s_cmpk_lt_u32 s88, 0x1f0
	s_cbranch_scc1 .Lidxsc_lo
	s_addk_i32 s88, 0xfe10
	s_mov_b64 s[90:91], s[92:93]
.Lidxsc_lo:
	s_mul_i32 s88, s88, 0x42000
	s_add_u32 s90, s90, s88
	s_addc_u32 s91, s91, 0
	s_sub_u32 s92, s90, 0x2000
	s_subb_u32 s93, s91, 0
	s_sub_u32 s94, s90, 0x1000
	s_subb_u32 s95, s91, 0
	v_lshl_add_u64 v[248:249], s[90:91], 0, v[250:251]
	v_lshl_add_u64 v[2:3], s[70:71], 0, v[2:3]
	v_and_b32_e32 v4, 48, v86
	v_mov_b32_e32 v5, v1
	v_lshl_add_u64 v[10:11], v[2:3], 0, v[4:5]
	v_lshlrev_b64 v[2:3], 5, v[0:1]
	v_lshl_add_u64 v[6:7], s[74:75], 0, v[2:3]
	global_load_dwordx4 v[38:41], v[10:11], off
	global_load_dwordx4 v[34:37], v[10:11], off offset:64
	global_load_dwordx4 v[2:5], v[6:7], off offset:16
	s_nop 0
	global_load_dwordx4 v[6:9], v[6:7], off
	s_nop 0
	global_load_dwordx4 v[30:33], v[10:11], off offset:128
	global_load_dwordx4 v[26:29], v[10:11], off offset:192
	global_load_dwordx4 v[22:25], v[10:11], off offset:256
	global_load_dwordx4 v[18:21], v[10:11], off offset:320
	global_load_dwordx4 v[14:17], v[10:11], off offset:384
	s_nop 0
	global_load_dwordx4 v[10:13], v[10:11], off offset:448
	s_movk_i32 s2, 0x2840
	v_cmp_gt_i32_e32 vcc, s2, v86
	v_add_u32_e32 v136, 0xffffff00, v86
	v_lshl_add_u32 v137, v86, 2, v96
	s_and_saveexec_b64 s[2:3], vcc
	s_cbranch_execz .LBB0_392
	v_add_u32_e32 v0, 0xffffff00, v86
	v_lshl_add_u32 v43, v86, 2, v96
	s_mov_b64 s[4:5], 0

; DI f32x4 mfma16(bf16x8 a, bf16x8 b, f32x4 c) { return __builtin_amdgcn_mfma_f32_16x16x32_bf16(a, b, c, 0, 0, 0); }
; template <int PASS, bool DIAG>
; DI void idx_tile(const bf16x8 kf, const bf16x8 (&qf)[8], const float (&wq)[8], int kt, int lm, int lg, int tq, bool selall, u32 bA, u32 pfx,
;                  u32* hist, u32* maskw, u32* cand, u32* ccnt) {
;   const f32x4 z4 = {0.f, 0.f, 0.f, 0.f};
;   f32x4 sc = z4;
; #pragma unroll
;   for (int j = 0; j < 8; ++j) {
;     f32x4 d = mfma16(kf, qf[j], z4);
; #pragma unroll
;     for (int r = 0; r < 4; ++r) sc[r] += wq[j] * fmaxf(d[r], 0.f);
;   }
;   u32 selbits = 0u;
; #pragma unroll
;   for (int r = 0; r < 4; ++r) {
;     const int key = kt * 16 + lg * 4 + r;
;     const bool valid = !DIAG || key <= tq;
;     const u32 bits = __float_as_uint(sc[r]);
;     const u32 u = bits ^ ((u32)((int)bits >> 31) | 0x80000000u);
;     if (PASS == 0) {
;       if (valid) { const u32 bin = u >> 22; atomicAdd(&hist[lm * 512 + (bin >> 1)], 1u << ((bin & 1) * 16)); }
; template <int PASS>
; DI void idx_pass(const u16* kp, const bf16x8 (&qf)[8], const float (&wq)[8], int wave, int ntile, int lm, int lg, int tq, bool selall,
;                  u32 bA, u32 pfx, u32* hist, u32* maskw, u32* cand, u32* ccnt) {
;   auto ldk = [&](int t) { return *(const bf16x8*)(kp + (size_t)(t < ntile ? t : 0) * 512); };
;   int kt = wave;
;   bf16x8 ka = ldk(kt), kb = ldk(kt + 4);
;   for (; kt + 4 < ntile - 1; kt += 8) {
;     const bf16x8 kc = ldk(kt + 8), kd = ldk(kt + 12);
;     idx_tile<PASS, false>(ka, qf, wq, kt, lm, lg, tq, selall, bA, pfx, hist, maskw, cand, ccnt);
;     idx_tile<PASS, false>(kb, qf, wq, kt + 4, lm, lg, tq, selall, bA, pfx, hist, maskw, cand, ccnt);
;     ka = kc; kb = kd;
;   }
.LBB0_392:
	s_or_b64 exec, exec, s[2:3]
	v_bfe_u32 v54, v86, 4, 2
	s_movk_i32 s2, 0x50
	v_and_b32_e32 v141, 63, v86
	v_mul_u32_u24_e32 v89, 0x1080, v42
	v_lshlrev_b32_e32 v43, 3, v54
	v_cmp_gt_i32_e32 vcc, s2, v86
	s_and_saveexec_b64 s[2:3], vcc
	v_lshl_add_u32 v0, v86, 2, v96
	ds_write_b32 v0, v1 offset:49408
	s_or_b64 exec, exec, s[2:3]
	s_waitcnt lgkmcnt(0)
	s_barrier
	s_load_dwordx16 s[60:75], s[0:1], 0x108
	v_mul_u32_u24_e32 v0, 0x21000, v42
	v_ashrrev_i32_e32 v109, 6, v86
	v_lshlrev_b32_e32 v0, 1, v0
	v_cmp_le_i32_e32 vcc, v109, v97
	s_waitcnt lgkmcnt(0)
	v_lshl_add_u64 v[44:45], s[72:73], 0, v[0:1]
	v_lshlrev_b32_e32 v0, 6, v88
	v_lshl_add_u64 v[44:45], v[44:45], 0, v[0:1]
	v_lshlrev_b32_e32 v0, 1, v43
	v_cndmask_b32_e32 v42, 0, v109, vcc
	v_lshl_add_u64 v[90:91], v[44:45], 0, v[0:1]
	v_ashrrev_i32_e32 v43, 31, v42
	v_add_u32_e32 v0, 4, v109
	v_lshlrev_b64 v[42:43], 10, v[42:43]
	v_cmp_le_i32_e32 vcc, v0, v97
	v_lshl_add_u64 v[92:93], v[90:91], 0, v[42:43]
	v_mov_b32_e32 v110, v0
	v_cndmask_b32_e32 v42, 0, v0, vcc
	v_ashrrev_i32_e32 v43, 31, v42
	v_lshlrev_b64 v[42:43], 10, v[42:43]
	v_lshl_add_u64 v[94:95], v[90:91], 0, v[42:43]
	global_load_dwordx4 v[42:45], v[92:93], off
	global_load_dwordx4 v[50:53], v[94:95], off
	v_cmp_lt_i32_e32 vcc, v0, v97
	v_mov_b32_e32 v111, v109
	s_and_saveexec_b64 s[2:3], vcc
	s_cbranch_execz .LBB0_398
	v_mov_b32_e32 v55, v88
	s_waitcnt vmcnt(8)
	v_mov_b32_e32 v56, v8
	v_mov_b32_e32 v57, v8
	v_mov_b32_e32 v58, v9
	v_mov_b32_e32 v59, v9
	v_mov_b32_e32 v60, v2
	v_mov_b32_e32 v61, v2
	v_mov_b32_e32 v62, v3
	v_mov_b32_e32 v63, v3
	v_mov_b32_e32 v64, v4
	v_mov_b32_e32 v65, v4
	v_mov_b32_e32 v66, v5
	v_mov_b32_e32 v67, v5
	s_mov_b64 s[6:7], 0
	v_mov_b32_e32 v111, v109
	s_waitcnt vmcnt(0)
.LBB0_396:
	s_waitcnt vmcnt(2)
	v_mov_b64_e32 v[70:71], v[44:45]
	v_mov_b64_e32 v[68:69], v[42:43]
	v_mov_b32_e32 v46, v111
	v_add_u32_e32 v111, 8, v46
	v_cmp_le_i32_e64 s[4:5], v111, v97
	v_add_u32_e32 v110, 12, v46
	v_mfma_f32_16x16x32_bf16 v[72:75], v[68:71], v[38:41], 0
	v_cndmask_b32_e64 v42, 0, v111, s[4:5]
	v_cmp_le_i32_e64 s[4:5], v110, v97
	v_ashrrev_i32_e32 v43, 31, v42
	v_lshlrev_b64 v[42:43], 10, v[42:43]
	v_cndmask_b32_e64 v46, 0, v110, s[4:5]
	s_nop 2
	v_max_f32_e32 v72, 0, v72
	v_fma_f32 v76, v6, v72, 0
	v_max_f32_e32 v72, 0, v73
	v_fma_f32 v77, v6, v72, 0
	v_max_f32_e32 v72, 0, v74
	v_fma_f32 v78, v6, v72, 0
	v_max_f32_e32 v72, 0, v75
	v_fma_f32 v79, v6, v72, 0
	v_mfma_f32_16x16x32_bf16 v[72:75], v[68:71], v[34:37], 0
	v_ashrrev_i32_e32 v47, 31, v46
	v_lshlrev_b64 v[46:47], 10, v[46:47]
	v_lshl_add_u64 v[42:43], v[90:91], 0, v[42:43]
	v_lshl_add_u64 v[46:47], v[90:91], 0, v[46:47]
	global_load_dwordx4 v[42:45], v[42:43], off
	s_nop 2
	v_max_f32_e32 v72, 0, v72
	v_mul_f32_e32 v80, v7, v72
	v_max_f32_e32 v72, 0, v73
	v_mul_f32_e32 v81, v7, v72
	v_max_f32_e32 v72, 0, v74
	v_mul_f32_e32 v82, v7, v72
	v_max_f32_e32 v72, 0, v75
	v_mul_f32_e32 v83, v7, v72
	v_mfma_f32_16x16x32_bf16 v[72:75], v[68:71], v[30:33], 0
	v_add_f32_e64 v76, v76, v80
	v_add_f32_e64 v77, v77, v81
	global_load_dwordx4 v[46:49], v[46:47], off
	v_cmp_ge_i32_e64 s[4:5], v110, v97
	s_or_b64 s[6:7], s[4:5], s[6:7]
	s_nop 2
	v_max_f32_e32 v84, 0, v72
	v_max_f32_e32 v85, 0, v73
	v_max_f32_e32 v98, 0, v74
	v_max_f32_e32 v99, 0, v75
	v_mfma_f32_16x16x32_bf16 v[72:75], v[68:71], v[26:29], 0
	v_fma_f32 v76, v56, v84, v76
	v_fma_f32 v77, v57, v85, v77
	s_nop 5
	v_max_f32_e32 v100, 0, v72
	v_max_f32_e32 v101, 0, v73
	v_max_f32_e32 v102, 0, v74
	v_max_f32_e32 v103, 0, v75
	v_mfma_f32_16x16x32_bf16 v[72:75], v[68:71], v[22:25], 0
	v_fma_f32 v76, v58, v100, v76
	v_fma_f32 v77, v59, v101, v77
	s_nop 5
	v_max_f32_e32 v104, 0, v72
	v_max_f32_e32 v105, 0, v73
	v_max_f32_e32 v106, 0, v74
	v_max_f32_e32 v107, 0, v75
	v_mfma_f32_16x16x32_bf16 v[72:75], v[68:71], v[18:21], 0
	v_fma_f32 v76, v60, v104, v76
	v_fma_f32 v77, v61, v105, v77
	s_nop 5
	v_max_f32_e32 v112, 0, v72
	v_max_f32_e32 v113, 0, v73
	v_max_f32_e32 v114, 0, v74
	v_max_f32_e32 v115, 0, v75
	v_mfma_f32_16x16x32_bf16 v[72:75], v[68:71], v[14:17], 0
	v_fma_f32 v76, v62, v112, v76
	v_fma_f32 v77, v63, v113, v77
	v_mfma_f32_16x16x32_bf16 v[68:71], v[68:71], v[10:13], 0
	s_nop 4
	v_max_f32_e32 v72, 0, v72
	v_max_f32_e32 v73, 0, v73
	s_nop 0
	v_max_f32_e32 v68, 0, v68
	v_max_f32_e32 v69, 0, v69
	v_pk_fma_f32 v[72:73], v[64:65], v[72:73], v[76:77]
	v_pk_fma_f32 v[68:69], v[66:67], v[68:69], v[72:73]
	v_mov_b32_e32 v168, v68
	v_mov_b32_e32 v169, v69
	v_ashrrev_i32_e32 v73, 31, v68
	v_ashrrev_i32_e32 v72, 31, v69
	v_or_b32_e32 v73, 0x80000000, v73
	v_or_b32_e32 v72, 0x80000000, v72
	v_xor_b32_e32 v68, v73, v68
	v_xor_b32_e32 v69, v72, v69
	v_alignbit_b32 v73, v88, v68, 23
	v_lshrrev_b32_e32 v68, 18, v68
	v_alignbit_b32 v72, v55, v69, 23
	v_and_b32_e32 v68, 16, v68
	v_lshrrev_b32_e32 v69, 18, v69
	v_lshl_add_u32 v73, v73, 2, v96
	v_lshlrev_b32_e64 v68, v68, 1
	v_and_b32_e32 v69, 16, v69
	ds_add_u32 v73, v68
	v_lshl_add_u32 v68, v72, 2, v96
	v_lshlrev_b32_e64 v69, v69, 1
	ds_add_u32 v68, v69
	v_pk_add_f32 v[68:69], v[78:79], v[82:83]
	v_max_f32_e32 v74, 0, v74
	v_pk_fma_f32 v[68:69], v[56:57], v[98:99], v[68:69]
	v_max_f32_e32 v75, 0, v75
	v_pk_fma_f32 v[68:69], v[58:59], v[102:103], v[68:69]
	v_pk_fma_f32 v[68:69], v[60:61], v[106:107], v[68:69]
	v_pk_fma_f32 v[68:69], v[62:63], v[114:115], v[68:69]
	v_max_f32_e32 v70, 0, v70
	v_max_f32_e32 v71, 0, v71
	v_pk_fma_f32 v[68:69], v[64:65], v[74:75], v[68:69]
	s_waitcnt vmcnt(4)
; DI f32x4 mfma16(bf16x8 a, bf16x8 b, f32x4 c) { return __builtin_amdgcn_mfma_f32_16x16x32_bf16(a, b, c, 0, 0, 0); }
; template <int PASS, bool DIAG>
; DI void idx_tile(const bf16x8 kf, const bf16x8 (&qf)[8], const float (&wq)[8], int kt, int lm, int lg, int tq, bool selall, u32 bA, u32 pfx,
;                  u32* hist, u32* maskw, u32* cand, u32* ccnt) {
;   const f32x4 z4 = {0.f, 0.f, 0.f, 0.f};
;   f32x4 sc = z4;
; #pragma unroll
;   for (int j = 0; j < 8; ++j) {
;     f32x4 d = mfma16(kf, qf[j], z4);
; #pragma unroll
;     for (int r = 0; r < 4; ++r) sc[r] += wq[j] * fmaxf(d[r], 0.f);
;   }
;   u32 selbits = 0u;
; #pragma unroll
;   for (int r = 0; r < 4; ++r) {
;     const int key = kt * 16 + lg * 4 + r;
;     const bool valid = !DIAG || key <= tq;
;     const u32 bits = __float_as_uint(sc[r]);
;     const u32 u = bits ^ ((u32)((int)bits >> 31) | 0x80000000u);
;     if (PASS == 0) {
;       if (valid) { const u32 bin = u >> 22; atomicAdd(&hist[lm * 512 + (bin >> 1)], 1u << ((bin & 1) * 16)); }
; template <int PASS>
; DI void idx_pass(const u16* kp, const bf16x8 (&qf)[8], const float (&wq)[8], int wave, int ntile, int lm, int lg, int tq, bool selall,
;                  u32 bA, u32 pfx, u32* hist, u32* maskw, u32* cand, u32* ccnt) {
;   auto ldk = [&](int t) { return *(const bf16x8*)(kp + (size_t)(t < ntile ? t : 0) * 512); };
;   int kt = wave;
;   bf16x8 ka = ldk(kt), kb = ldk(kt + 4);
;   for (; kt + 4 < ntile - 1; kt += 8) {
;     const bf16x8 kc = ldk(kt + 8), kd = ldk(kt + 12);
;     idx_tile<PASS, false>(ka, qf, wq, kt, lm, lg, tq, selall, bA, pfx, hist, maskw, cand, ccnt);
;     idx_tile<PASS, false>(kb, qf, wq, kt + 4, lm, lg, tq, selall, bA, pfx, hist, maskw, cand, ccnt);
;     ka = kc; kb = kd;
;   }
	v_mfma_f32_16x16x32_bf16 v[112:115], v[50:53], v[14:17], 0
	v_fma_f32 v68, v66, v70, v68
	v_fma_f32 v69, v67, v71, v69
	v_mov_b32_e32 v170, v68
	v_mov_b32_e32 v171, v69
	v_lshl_add_u32 v172, v111, 10, v250
	global_store_dwordx4 v172, v[168:171], s[92:93]
	v_ashrrev_i32_e32 v71, 31, v68
	v_ashrrev_i32_e32 v70, 31, v69
	v_or_b32_e32 v71, 0x80000000, v71
	v_or_b32_e32 v70, 0x80000000, v70
	v_xor_b32_e32 v68, v71, v68
	v_xor_b32_e32 v69, v70, v69
	v_alignbit_b32 v71, v88, v68, 23
	v_lshrrev_b32_e32 v68, 18, v68
	v_alignbit_b32 v70, v55, v69, 23
	v_and_b32_e32 v68, 16, v68
	v_lshrrev_b32_e32 v69, 18, v69
	v_lshl_add_u32 v71, v71, 2, v96
	v_lshlrev_b32_e64 v68, v68, 1
	v_and_b32_e32 v69, 16, v69
	ds_add_u32 v71, v68
	v_lshl_add_u32 v68, v70, 2, v96
	v_lshlrev_b32_e64 v69, v69, 1
	ds_add_u32 v68, v69
	v_mfma_f32_16x16x32_bf16 v[68:71], v[50:53], v[38:41], 0
	s_nop 7
	v_max_f32_e32 v68, 0, v68
	v_fma_f32 v82, v6, v68, 0
	v_max_f32_e32 v68, 0, v69
	v_fma_f32 v83, v6, v68, 0
	v_max_f32_e32 v68, 0, v70
	v_fma_f32 v74, v6, v68, 0
	v_max_f32_e32 v68, 0, v71
	v_fma_f32 v75, v6, v68, 0
	v_mfma_f32_16x16x32_bf16 v[68:71], v[50:53], v[34:37], 0
	s_nop 7
	v_max_f32_e32 v68, 0, v68
	v_mul_f32_e32 v84, v7, v68
	v_max_f32_e32 v68, 0, v69
	v_mul_f32_e32 v85, v7, v68
	v_max_f32_e32 v68, 0, v70
	v_mul_f32_e32 v78, v7, v68
	v_max_f32_e32 v68, 0, v71
	v_mul_f32_e32 v79, v7, v68
	v_mfma_f32_16x16x32_bf16 v[68:71], v[50:53], v[30:33], 0
	s_nop 7
	v_max_f32_e32 v98, 0, v68
	v_max_f32_e32 v99, 0, v69
	v_max_f32_e32 v80, 0, v70
	v_max_f32_e32 v81, 0, v71
	v_mfma_f32_16x16x32_bf16 v[68:71], v[50:53], v[26:29], 0
	s_nop 7
	v_max_f32_e32 v100, 0, v68
	v_max_f32_e32 v101, 0, v69
	v_max_f32_e32 v76, 0, v70
	v_max_f32_e32 v77, 0, v71
	v_mfma_f32_16x16x32_bf16 v[68:71], v[50:53], v[22:25], 0
	s_nop 7
	v_max_f32_e32 v102, 0, v68
	v_max_f32_e32 v103, 0, v69
	v_max_f32_e32 v68, v70, v70
	v_max_f32_e32 v69, v71, v71
	v_mfma_f32_16x16x32_bf16 v[70:73], v[50:53], v[18:21], 0
	v_max_f32_e32 v68, 0, v68
	v_max_f32_e32 v69, 0, v69
	v_mfma_f32_16x16x32_bf16 v[50:53], v[50:53], v[10:13], 0
	s_nop 4
	v_max_f32_e32 v104, 0, v70
	v_max_f32_e32 v105, 0, v71
	v_max_f32_e32 v70, v72, v72
	v_max_f32_e32 v72, v112, v112
	v_max_f32_e32 v112, 0, v50
	v_max_f32_e32 v106, 0, v72
	v_max_f32_e32 v72, v113, v113
	v_max_f32_e32 v113, 0, v51
	v_max_f32_e32 v50, v52, v52
	v_max_f32_e32 v51, v53, v53
	v_pk_add_f32 v[52:53], v[82:83], v[84:85]
	v_max_f32_e32 v107, 0, v72
	v_pk_fma_f32 v[52:53], v[56:57], v[98:99], v[52:53]
	v_pk_fma_f32 v[52:53], v[58:59], v[100:101], v[52:53]
	v_max_f32_e32 v70, 0, v70
	v_pk_fma_f32 v[52:53], v[60:61], v[102:103], v[52:53]
	v_max_f32_e32 v71, 0, v73
	v_pk_fma_f32 v[52:53], v[62:63], v[104:105], v[52:53]
	v_pk_fma_f32 v[52:53], v[64:65], v[106:107], v[52:53]
	v_pk_fma_f32 v[52:53], v[66:67], v[112:113], v[52:53]
	v_mov_b32_e32 v176, v52
	v_mov_b32_e32 v177, v53
	v_max_f32_e32 v72, 0, v114
	v_ashrrev_i32_e32 v83, 31, v52
	v_ashrrev_i32_e32 v82, 31, v53
	v_or_b32_e32 v83, 0x80000000, v83
	v_or_b32_e32 v82, 0x80000000, v82
	v_xor_b32_e32 v52, v83, v52
	v_xor_b32_e32 v53, v82, v53
	v_alignbit_b32 v83, v88, v52, 23
	v_lshrrev_b32_e32 v52, 18, v52
	v_alignbit_b32 v82, v55, v53, 23
	v_and_b32_e32 v52, 16, v52
	v_lshrrev_b32_e32 v53, 18, v53
	v_lshl_add_u32 v83, v83, 2, v96
	v_lshlrev_b32_e64 v52, v52, 1
	v_and_b32_e32 v53, 16, v53
	ds_add_u32 v83, v52
	v_lshl_add_u32 v52, v82, 2, v96
	v_lshlrev_b32_e64 v53, v53, 1
	ds_add_u32 v52, v53
	v_pk_add_f32 v[52:53], v[74:75], v[78:79]
	v_max_f32_e32 v73, 0, v115
	v_pk_fma_f32 v[52:53], v[56:57], v[80:81], v[52:53]
	v_max_f32_e32 v50, 0, v50
	v_pk_fma_f32 v[52:53], v[58:59], v[76:77], v[52:53]
	v_max_f32_e32 v51, 0, v51
	v_pk_fma_f32 v[52:53], v[60:61], v[68:69], v[52:53]
	s_nop 0
	v_pk_fma_f32 v[52:53], v[62:63], v[70:71], v[52:53]
	s_nop 0
	v_pk_fma_f32 v[52:53], v[64:65], v[72:73], v[52:53]
	s_nop 0
	v_pk_fma_f32 v[50:51], v[66:67], v[50:51], v[52:53]
	v_mov_b32_e32 v178, v50
	v_mov_b32_e32 v179, v51
	global_store_dwordx4 v172, v[176:179], s[94:95]
	s_nop 0
	v_ashrrev_i32_e32 v53, 31, v50
	v_ashrrev_i32_e32 v52, 31, v51
	v_or_b32_e32 v53, 0x80000000, v53
	v_or_b32_e32 v52, 0x80000000, v52
	v_xor_b32_e32 v50, v53, v50
	v_xor_b32_e32 v51, v52, v51
	v_alignbit_b32 v53, v88, v50, 23
	v_lshrrev_b32_e32 v50, 18, v50
	v_alignbit_b32 v52, v55, v51, 23
	v_and_b32_e32 v50, 16, v50
	v_lshrrev_b32_e32 v51, 18, v51
	v_lshl_add_u32 v53, v53, 2, v96
	v_lshlrev_b32_e64 v50, v50, 1
	v_and_b32_e32 v51, 16, v51
	ds_add_u32 v53, v50
	v_lshl_add_u32 v50, v52, 2, v96
	v_lshlrev_b32_e64 v51, v51, 1
	ds_add_u32 v50, v51
	s_waitcnt vmcnt(2)
	v_mov_b64_e32 v[52:53], v[48:49]
	v_mov_b64_e32 v[50:51], v[46:47]
	s_andn2_b64 exec, exec, s[6:7]
	s_cbranch_execnz .LBB0_396
	s_or_b64 exec, exec, s[6:7]
	v_mov_b64_e32 v[52:53], v[48:49]
	v_mov_b64_e32 v[50:51], v[46:47]

; template <int PASS>
; DI void idx_pass(const u16* kp, const bf16x8 (&qf)[8], const float (&wq)[8], int wave, int ntile, int lm, int lg, int tq, bool selall,
;                  u32 bA, u32 pfx, u32* hist, u32* maskw, u32* cand, u32* ccnt) {
;   auto ldk = [&](int t) { return *(const bf16x8*)(kp + (size_t)(t < ntile ? t : 0) * 512); };
;   int kt = wave;
;   bf16x8 ka = ldk(kt), kb = ldk(kt + 4);
; DI void idx_job(const Params& p, int b, int qg, unsigned char* smem) {
;     ...
;   for (int i = tid; i < 8192; i += 256) hist[i] = 0u;
;   __syncthreads();
;   idx_pass<1>(kp, qf, wq, wave, ntile, lm, lg, tq, selall, binA[lm], 0u, hist, maskw, cand, ccnt);
.LBB0_602:
	s_or_b64 exec, exec, s[2:3]
	s_waitcnt lgkmcnt(0)
	s_barrier
	v_lshlrev_b32_e32 v160, 10, v109
	v_mov_b32_e32 v161, 0
	v_lshl_add_u64 v[160:161], v[248:249], 0, v[160:161]
	v_mov_b32_e32 v162, 0x1000
	v_mov_b32_e32 v163, 0
	v_lshl_add_u64 v[162:163], v[160:161], 0, v[162:163]
	v_cndmask_b32_e32 v160, v92, v160, vcc
	v_cndmask_b32_e32 v161, v93, v161, vcc
	v_cndmask_b32_e32 v162, v94, v162, vcc
	v_cndmask_b32_e32 v163, v95, v163, vcc
	global_load_dwordx4 v[42:45], v[160:161], off
	global_load_dwordx4 v[46:49], v[162:163], off
	v_lshl_add_u32 v136, v88, 2, v96
	ds_read_b32 v137, v136 offset:49472
	v_mov_b32_e32 v79, v0
	v_mov_b32_e32 v153, v109
	s_and_saveexec_b64 s[2:3], vcc
	s_cbranch_execz .LBB0_622
	v_lshl_add_u32 v154, v88, 11, v96
	s_mov_b64 s[6:7], 0
	v_mov_b32_e32 v153, v109
	s_branch .LBB0_605

; template <int PASS, bool DIAG>
; DI void idx_tile(const bf16x8 kf, const bf16x8 (&qf)[8], const float (&wq)[8], int kt, int lm, int lg, int tq, bool selall, u32 bA, u32 pfx,
;                  u32* hist, u32* maskw, u32* cand, u32* ccnt) {
;     ...
;   for (int r = 0; r < 4; ++r) {
;     const int key = kt * 16 + lg * 4 + r;
;     const bool valid = !DIAG || key <= tq;
;     const u32 bits = __float_as_uint(sc[r]);
;     const u32 u = bits ^ ((u32)((int)bits >> 31) | 0x80000000u);
;     if (PASS == 0) {
;       if (valid) { const u32 bin = u >> 22; atomicAdd(&hist[lm * 512 + (bin >> 1)], 1u << ((bin & 1) * 16)); }
;     } else if (PASS == 1) {
;       if (valid && (u >> 22) == bA) { const u32 bin = (u >> 12) & 1023u; atomicAdd(&hist[lm * 512 + (bin >> 1)], 1u << ((bin & 1) * 16)); }
; template <int PASS>
; DI void idx_pass(const u16* kp, const bf16x8 (&qf)[8], const float (&wq)[8], int wave, int ntile, int lm, int lg, int tq, bool selall,
;                  u32 bA, u32 pfx, u32* hist, u32* maskw, u32* cand, u32* ccnt) {
;     ...
;   for (; kt + 4 < ntile - 1; kt += 8) {
;     const bf16x8 kc = ldk(kt + 8), kd = ldk(kt + 12);
;     idx_tile<PASS, false>(ka, qf, wq, kt, lm, lg, tq, selall, bA, pfx, hist, maskw, cand, ccnt);
;     idx_tile<PASS, false>(kb, qf, wq, kt + 4, lm, lg, tq, selall, bA, pfx, hist, maskw, cand, ccnt);
;     ka = kc; kb = kd;
;   }
.LBB0_605:
	s_waitcnt vmcnt(1)
	v_mov_b64_e32 v[84:85], v[44:45]
	v_mov_b64_e32 v[82:83], v[42:43]
	v_mov_b32_e32 v44, v153
	v_add_u32_e32 v153, 8, v44
	v_cmp_le_i32_e64 s[4:5], v153, v97
	v_add_u32_e32 v44, 12, v44
	v_cmp_lt_i32_e64 s[94:95], v44, v97
	v_cndmask_b32_e64 v42, 0, v153, s[4:5]
	v_cmp_le_i32_e64 s[4:5], v44, v97
	v_ashrrev_i32_e32 v43, 31, v42
	v_lshlrev_b64 v[42:43], 10, v[42:43]
	v_cndmask_b32_e64 v44, 0, v44, s[4:5]
	v_ashrrev_i32_e32 v45, 31, v44
	v_lshlrev_b64 v[44:45], 10, v[44:45]
	v_cndmask_b32_e64 v160, v90, v248, s[94:95]
	v_cndmask_b32_e64 v161, v91, v249, s[94:95]
	v_lshl_add_u64 v[42:43], v[160:161], 0, v[42:43]
	v_lshl_add_u64 v[50:51], v[160:161], 0, v[44:45]
	global_load_dwordx4 v[42:45], v[42:43], off
	s_nop 0
	global_load_dwordx4 v[50:53], v[50:51], off
	v_ashrrev_i32_e32 v58, 31, v82
	v_bitop3_b32 v54, v58, v82, s39 bitop3:0x36
	v_lshrrev_b32_e32 v58, 22, v54
	s_waitcnt lgkmcnt(0)
	v_cmp_eq_u32_e64 s[4:5], v58, v137
	s_and_saveexec_b64 s[8:9], s[4:5]
	s_cbranch_execz .Lidx1_skip0
	v_lshrrev_b32_e32 v58, 8, v54
	v_lshrrev_b32_e32 v54, 11, v54
	v_and_b32_e32 v58, 16, v58
	v_and_b32_e32 v54, 0x7fc, v54
	v_lshlrev_b32_e64 v58, v58, 1
	v_add_u32_e32 v54, v154, v54
	ds_add_u32 v54, v58
.Lidx1_skip0:
	s_or_b64 exec, exec, s[8:9]
	v_ashrrev_i32_e32 v58, 31, v83
	v_bitop3_b32 v54, v58, v83, s39 bitop3:0x36
	v_lshrrev_b32_e32 v58, 22, v54
	v_cmp_eq_u32_e64 s[4:5], v58, v137
	s_and_saveexec_b64 s[8:9], s[4:5]
	s_cbranch_execz .Lidx1_skip1
	v_lshrrev_b32_e32 v58, 8, v54
	v_lshrrev_b32_e32 v54, 11, v54
	v_and_b32_e32 v58, 16, v58
	v_and_b32_e32 v54, 0x7fc, v54
	v_lshlrev_b32_e64 v58, v58, 1
	v_add_u32_e32 v54, v154, v54
	ds_add_u32 v54, v58
.Lidx1_skip1:
	s_or_b64 exec, exec, s[8:9]
	v_ashrrev_i32_e32 v58, 31, v84
	v_bitop3_b32 v54, v58, v84, s39 bitop3:0x36
	v_lshrrev_b32_e32 v58, 22, v54
	v_cmp_eq_u32_e64 s[4:5], v58, v137
	s_and_saveexec_b64 s[8:9], s[4:5]
	s_cbranch_execz .Lidx1_skip2
	v_lshrrev_b32_e32 v58, 8, v54
	v_lshrrev_b32_e32 v54, 11, v54
	v_and_b32_e32 v58, 16, v58
	v_and_b32_e32 v54, 0x7fc, v54
	v_lshlrev_b32_e64 v58, v58, 1
	v_add_u32_e32 v54, v154, v54
	ds_add_u32 v54, v58
.Lidx1_skip2:
	s_or_b64 exec, exec, s[8:9]
	v_ashrrev_i32_e32 v58, 31, v85
	v_bitop3_b32 v54, v58, v85, s39 bitop3:0x36
	v_lshrrev_b32_e32 v58, 22, v54
	v_cmp_eq_u32_e64 s[4:5], v58, v137
	s_and_saveexec_b64 s[8:9], s[4:5]
	s_cbranch_execz .Lidx1_skip3
	v_lshrrev_b32_e32 v58, 8, v54
	v_lshrrev_b32_e32 v54, 11, v54
	v_and_b32_e32 v58, 16, v58
	v_and_b32_e32 v54, 0x7fc, v54
	v_lshlrev_b32_e64 v58, v58, 1
	v_add_u32_e32 v54, v154, v54
	ds_add_u32 v54, v58
.Lidx1_skip3:
	s_or_b64 exec, exec, s[8:9]
	s_waitcnt vmcnt(2)
	v_ashrrev_i32_e32 v58, 31, v46
	v_bitop3_b32 v54, v58, v46, s39 bitop3:0x36
	v_lshrrev_b32_e32 v58, 22, v54
	v_cmp_eq_u32_e64 s[4:5], v58, v137
	s_and_saveexec_b64 s[8:9], s[4:5]
	s_cbranch_execz .Lidx1_skip4
	v_lshrrev_b32_e32 v58, 8, v54
	v_lshrrev_b32_e32 v54, 11, v54
	v_and_b32_e32 v58, 16, v58
	v_and_b32_e32 v54, 0x7fc, v54
	v_lshlrev_b32_e64 v58, v58, 1
	v_add_u32_e32 v54, v154, v54
	ds_add_u32 v54, v58
.Lidx1_skip4:
	s_or_b64 exec, exec, s[8:9]
	v_ashrrev_i32_e32 v58, 31, v47
	v_bitop3_b32 v54, v58, v47, s39 bitop3:0x36
	v_lshrrev_b32_e32 v58, 22, v54
	v_cmp_eq_u32_e64 s[4:5], v58, v137
	s_and_saveexec_b64 s[8:9], s[4:5]
	s_cbranch_execz .Lidx1_skip5
	v_lshrrev_b32_e32 v58, 8, v54
	v_lshrrev_b32_e32 v54, 11, v54
	v_and_b32_e32 v58, 16, v58
	v_and_b32_e32 v54, 0x7fc, v54
	v_lshlrev_b32_e64 v58, v58, 1
	v_add_u32_e32 v54, v154, v54
	ds_add_u32 v54, v58
.Lidx1_skip5:
	s_or_b64 exec, exec, s[8:9]
	v_ashrrev_i32_e32 v58, 31, v48
	v_bitop3_b32 v54, v58, v48, s39 bitop3:0x36
	v_lshrrev_b32_e32 v58, 22, v54
	v_cmp_eq_u32_e64 s[4:5], v58, v137
	s_and_saveexec_b64 s[8:9], s[4:5]
	s_cbranch_execz .Lidx1_skip6
	v_lshrrev_b32_e32 v58, 8, v54
	v_lshrrev_b32_e32 v54, 11, v54
	v_and_b32_e32 v58, 16, v58
	v_and_b32_e32 v54, 0x7fc, v54
	v_lshlrev_b32_e64 v58, v58, 1
	v_add_u32_e32 v54, v154, v54
	ds_add_u32 v54, v58
.Lidx1_skip6:
	s_or_b64 exec, exec, s[8:9]
	v_ashrrev_i32_e32 v58, 31, v49
	v_bitop3_b32 v54, v58, v49, s39 bitop3:0x36
	v_lshrrev_b32_e32 v58, 22, v54
	v_cmp_eq_u32_e64 s[4:5], v58, v137
	s_and_saveexec_b64 s[8:9], s[4:5]
	s_cbranch_execz .Lidx1_skip7
	v_lshrrev_b32_e32 v58, 8, v54
	v_lshrrev_b32_e32 v54, 11, v54
	v_and_b32_e32 v58, 16, v58
	v_and_b32_e32 v54, 0x7fc, v54
	v_lshlrev_b32_e64 v58, v58, 1
	v_add_u32_e32 v54, v154, v54
	ds_add_u32 v54, v58
.Lidx1_skip7:
	s_or_b64 exec, exec, s[8:9]
	s_branch .LBB0_604
